# S5 item setup: coefficients evaluated once per state lane and gathered with bpermute, B rows of all 8 tiles loaded up front (replaces 7 of 8 per-tile evaluations); no s5 touch-prefetch
# speedup vs baseline: 1.0081x; 1.0041x over previous
.LBB0_782:
	s_or_b32 s0, s25, s7
	s_and_b32 s53, s25, 1
	s_bfe_u32 s52, s0, 0x70001
	s_lshl_b32 s0, s53, 7
	s_or_b32 s0, s0, s8
	s_or_b32 s2, s52, s0
	s_ashr_i32 s3, s2, 31
	s_lshl_b64 s[12:13], s[2:3], 8
	s_add_u32 s0, s66, s12
	s_addc_u32 s1, s67, s13
	s_add_u32 s12, s68, s12
	s_addc_u32 s13, s69, s13
	s_lshl_b64 s[2:3], s[2:3], 2
	s_add_u32 s2, s70, s2
	s_addc_u32 s3, s71, s3
	global_load_dword v2, v3, s[2:3]
	s_or_b32 s46, s52, s9
	s_ashr_i32 s47, s46, 31
	s_lshl_b64 s[46:47], s[46:47], 10
	v_mov_b32_e32 v197, s47
	v_or_b32_e32 v196, s46, v92
	v_lshlrev_b64 v[196:197], 2, v[196:197]
	v_lshl_add_u64 v[198:199], v[112:113], 0, v[196:197]
	v_lshl_add_u64 v[200:201], v[114:115], 0, v[196:197]
	s_and_saveexec_b64 s[14:15], s[40:41]
	global_load_dwordx4 v[132:135], v[198:199], off offset:16
	global_load_dwordx4 v[136:139], v[198:199], off
	global_load_dwordx4 v[140:143], v[200:201], off offset:16
	global_load_dwordx4 v[144:147], v[200:201], off
	global_load_dwordx4 v[148:151], v[198:199], off offset:528
	global_load_dwordx4 v[152:155], v[198:199], off offset:512
	global_load_dwordx4 v[156:159], v[200:201], off offset:528
	global_load_dwordx4 v[160:163], v[200:201], off offset:512
	global_load_dwordx4 v[164:167], v[198:199], off offset:1040
	global_load_dwordx4 v[168:171], v[198:199], off offset:1024
	global_load_dwordx4 v[172:175], v[200:201], off offset:1040
	global_load_dwordx4 v[176:179], v[200:201], off offset:1024
	global_load_dwordx4 v[180:183], v[198:199], off offset:1552
	global_load_dwordx4 v[184:187], v[198:199], off offset:1536
	global_load_dwordx4 v[188:191], v[200:201], off offset:1552
	global_load_dwordx4 v[192:195], v[200:201], off offset:1536
	global_load_dwordx4 v[36:39], v[198:199], off offset:2064
	global_load_dwordx4 v[40:43], v[198:199], off offset:2048
	global_load_dwordx4 v[44:47], v[200:201], off offset:2064
	global_load_dwordx4 v[48:51], v[200:201], off offset:2048
	global_load_dwordx4 v[52:55], v[198:199], off offset:2576
	global_load_dwordx4 v[56:59], v[198:199], off offset:2560
	global_load_dwordx4 v[60:63], v[200:201], off offset:2576
	global_load_dwordx4 v[64:67], v[200:201], off offset:2560
	global_load_dwordx4 v[68:71], v[198:199], off offset:3088
	global_load_dwordx4 v[72:75], v[198:199], off offset:3072
	global_load_dwordx4 v[76:79], v[200:201], off offset:3088
	global_load_dwordx4 v[80:83], v[200:201], off offset:3072
	global_load_dwordx4 v[228:231], v[198:199], off offset:3600
	global_load_dwordx4 v[232:235], v[198:199], off offset:3584
	global_load_dwordx4 v[236:239], v[200:201], off offset:3600
	global_load_dwordx4 v[240:243], v[200:201], off offset:3584
	s_mov_b64 exec, s[14:15]
	s_waitcnt vmcnt(32)
	v_mul_f32_e32 v4, 0x3fb8aa3b, v2
	v_fma_f32 v5, v2, s27, -v4
	v_rndne_f32_e32 v6, v4
	v_fmac_f32_e32 v5, 0x32a5705f, v2
	v_sub_f32_e32 v4, v4, v6
	v_add_f32_e32 v4, v4, v5
	v_exp_f32_e32 v4, v4
	v_cvt_i32_f32_e32 v5, v6
	v_cmp_ngt_f32_e32 vcc, s29, v2
	v_ldexp_f32 v4, v4, v5
	s_nop 0
	v_cndmask_b32_e32 v4, 0, v4, vcc
	v_cmp_nlt_f32_e32 vcc, s10, v2
	s_nop 1
	v_cndmask_b32_e32 v105, v223, v4, vcc
	v_lshlrev_b64 v[4:5], 2, v[0:1]
	v_lshl_add_u64 v[6:7], s[0:1], 0, v[4:5]
	v_lshl_add_u64 v[4:5], s[12:13], 0, v[4:5]
	global_load_dword v2, v[4:5], off
	global_load_dword v107, v[6:7], off
	s_waitcnt vmcnt(1)
	v_mul_f32_e32 v124, v105, v2
	v_and_b32_e32 v125, 0x7fffffff, v124
	v_cmp_nlt_f32_e64 s[2:3], |v124|, s11
	s_and_saveexec_b64 s[14:15], s[2:3]
	s_xor_b64 s[14:15], exec, s[14:15]
	s_cbranch_execz .LBB0_784
	v_lshrrev_b32_e32 v2, 23, v125
	v_add_u32_e32 v2, 0xffffff88, v2
	v_cmp_lt_u32_e32 vcc, 63, v2
	s_nop 1
	v_cndmask_b32_e32 v4, 0, v224, vcc
	v_add_u32_e32 v2, v4, v2
	v_cmp_lt_u32_e64 s[46:47], 31, v2
	s_nop 1
	v_cndmask_b32_e64 v4, 0, v250, s[46:47]
	v_add_u32_e32 v2, v4, v2
	v_cmp_lt_u32_e64 s[48:49], 31, v2
	s_nop 1
	v_cndmask_b32_e64 v4, 0, v250, s[48:49]
	v_add_u32_e32 v18, v4, v2
	v_and_b32_e32 v2, 0x7fffff, v125
	v_or_b32_e32 v16, 0x800000, v2
	v_mad_u64_u32 v[4:5], s[2:3], v16, s26, 0
	v_mov_b32_e32 v2, v5
	v_mad_u64_u32 v[6:7], s[2:3], v16, s34, v[2:3]
	v_mov_b32_e32 v2, v7
	v_mad_u64_u32 v[8:9], s[2:3], v16, s88, v[2:3]
	v_mov_b32_e32 v2, v9
	v_mad_u64_u32 v[10:11], s[2:3], v16, s89, v[2:3]
	v_mov_b32_e32 v2, v11
	v_mad_u64_u32 v[12:13], s[2:3], v16, s90, v[2:3]
	v_mov_b32_e32 v2, v13
	v_mad_u64_u32 v[14:15], s[2:3], v16, s91, v[2:3]
	v_mov_b32_e32 v2, v15
	v_mad_u64_u32 v[16:17], s[2:3], v16, s92, v[2:3]
	v_cndmask_b32_e32 v5, v14, v10, vcc
	v_cndmask_b32_e32 v2, v16, v12, vcc
	v_cndmask_b32_e32 v9, v17, v14, vcc
	v_cndmask_b32_e64 v7, v2, v5, s[46:47]
	v_cndmask_b32_e64 v2, v9, v2, s[46:47]
	v_cndmask_b32_e32 v9, v12, v8, vcc
	v_cndmask_b32_e64 v5, v5, v9, s[46:47]
	v_cndmask_b32_e32 v6, v10, v6, vcc
	v_cndmask_b32_e64 v2, v2, v7, s[48:49]
	v_cndmask_b32_e64 v7, v7, v5, s[48:49]
	v_sub_u32_e32 v11, 32, v18
	v_cndmask_b32_e64 v9, v9, v6, s[46:47]
	v_alignbit_b32 v12, v2, v7, v11
	v_cmp_eq_u32_e64 s[50:51], 0, v18
	v_cndmask_b32_e64 v5, v5, v9, s[48:49]
	v_cndmask_b32_e32 v4, v8, v4, vcc
	v_cndmask_b32_e64 v2, v12, v2, s[50:51]
	v_alignbit_b32 v10, v7, v5, v11
	v_cndmask_b32_e64 v4, v6, v4, s[46:47]
	v_cndmask_b32_e64 v7, v10, v7, s[50:51]
	v_bfe_u32 v13, v2, 29, 1
	v_cndmask_b32_e64 v4, v9, v4, s[48:49]
	v_alignbit_b32 v10, v2, v7, 30
	v_sub_u32_e32 v14, 0, v13
	v_alignbit_b32 v6, v5, v4, v11
	v_xor_b32_e32 v10, v10, v14
	v_cndmask_b32_e64 v5, v6, v5, s[50:51]
	v_alignbit_b32 v6, v7, v5, 30
	v_ffbh_u32_e32 v7, v10
	v_min_u32_e32 v7, 32, v7
	v_alignbit_b32 v4, v5, v4, 30
	v_xor_b32_e32 v6, v6, v14
	v_sub_u32_e32 v8, 31, v7
	v_xor_b32_e32 v4, v4, v14
	v_alignbit_b32 v9, v10, v6, v8
	v_alignbit_b32 v4, v6, v4, v8
	v_alignbit_b32 v5, v9, v4, 9
	v_ffbh_u32_e32 v6, v5
	v_min_u32_e32 v6, 32, v6
	v_lshrrev_b32_e32 v12, 29, v2
	v_not_b32_e32 v8, v6
	v_alignbit_b32 v4, v5, v4, v8
	v_lshlrev_b32_e32 v5, 31, v12
	v_or_b32_e32 v8, 0x33000000, v5
	v_add_lshl_u32 v6, v6, v7, 23
	v_lshrrev_b32_e32 v4, 9, v4
	v_sub_u32_e32 v6, v8, v6
	v_or_b32_e32 v5, 0.5, v5
	v_lshlrev_b32_e32 v7, 23, v7
	v_or_b32_e32 v4, v6, v4
	v_lshrrev_b32_e32 v6, 9, v9
	v_sub_u32_e32 v5, v5, v7
	v_or_b32_e32 v5, v6, v5
	v_mul_f32_e32 v6, 0x3fc90fda, v5
	v_fma_f32 v7, v5, s93, -v6
	v_fmac_f32_e32 v7, 0x33a22168, v5
	v_fmac_f32_e32 v7, 0x3fc90fda, v4
	v_lshrrev_b32_e32 v2, 30, v2
	v_add_f32_e32 v126, v6, v7
	v_add_u32_e32 v127, v13, v2
.LBB0_784:
	s_andn2_saveexec_b64 s[14:15], s[14:15]
	v_mul_f32_e64 v2, |v124|, s94
	v_rndne_f32_e32 v2, v2
	v_cvt_i32_f32_e32 v127, v2
	v_fma_f32 v126, v2, s95, |v124|
	v_fmac_f32_e32 v126, 0xb3a22168, v2
	v_fmac_f32_e32 v126, 0xa7c234c4, v2
	s_or_b64 exec, exec, s[14:15]
	v_lshlrev_b32_e32 v2, 2, v0
	global_load_dword v8, v2, s[12:13]
	global_load_dword v11, v2, s[0:1]
	s_waitcnt vmcnt(1)
	v_mul_f32_e32 v9, v105, v8
	v_and_b32_e32 v10, 0x7fffffff, v9
	v_cmp_nlt_f32_e64 s[2:3], |v9|, s11
	s_and_saveexec_b64 s[14:15], s[2:3]
	s_xor_b64 s[14:15], exec, s[14:15]
	s_cbranch_execz .LBB0_788
	v_lshrrev_b32_e32 v4, 23, v10
	v_add_u32_e32 v4, 0xffffff88, v4
	v_cmp_lt_u32_e32 vcc, 63, v4
	v_mov_b32_e32 v7, v3
	v_mov_b32_e32 v13, v3
	v_cndmask_b32_e32 v5, 0, v224, vcc
	v_add_u32_e32 v4, v5, v4
	v_cmp_lt_u32_e64 s[46:47], 31, v4
	v_mov_b32_e32 v15, v3
	v_mov_b32_e32 v17, v3
	v_cndmask_b32_e64 v5, 0, v250, s[46:47]
	v_add_u32_e32 v4, v5, v4
	v_cmp_lt_u32_e64 s[48:49], 31, v4
	v_mov_b32_e32 v19, v3
	v_mov_b32_e32 v21, v3
	v_cndmask_b32_e64 v5, 0, v250, s[48:49]
	v_add_u32_e32 v22, v5, v4
	v_and_b32_e32 v4, 0x7fffff, v10
	v_or_b32_e32 v23, 0x800000, v4
	v_mad_u64_u32 v[4:5], s[2:3], v23, s26, 0
	v_mov_b32_e32 v6, v5
	v_mad_u64_u32 v[6:7], s[2:3], v23, s34, v[6:7]
	v_mov_b32_e32 v12, v7
	v_mad_u64_u32 v[12:13], s[2:3], v23, s88, v[12:13]
	v_mov_b32_e32 v14, v13
	v_mad_u64_u32 v[14:15], s[2:3], v23, s89, v[14:15]
	v_mov_b32_e32 v16, v15
	v_mad_u64_u32 v[16:17], s[2:3], v23, s90, v[16:17]
	v_mov_b32_e32 v18, v17
	v_mad_u64_u32 v[18:19], s[2:3], v23, s91, v[18:19]
	v_mov_b32_e32 v20, v19
	v_mad_u64_u32 v[20:21], s[2:3], v23, s92, v[20:21]
	v_cndmask_b32_e32 v5, v18, v14, vcc
	v_cndmask_b32_e32 v7, v20, v16, vcc
	v_cndmask_b32_e32 v15, v21, v18, vcc
	v_cndmask_b32_e64 v13, v7, v5, s[46:47]
	v_cndmask_b32_e64 v7, v15, v7, s[46:47]
	v_cndmask_b32_e32 v15, v16, v12, vcc
	v_cndmask_b32_e64 v5, v5, v15, s[46:47]
	v_cndmask_b32_e32 v6, v14, v6, vcc
	v_cndmask_b32_e64 v7, v7, v13, s[48:49]
	v_cndmask_b32_e64 v13, v13, v5, s[48:49]
	v_sub_u32_e32 v16, 32, v22
	v_cndmask_b32_e64 v14, v15, v6, s[46:47]
	v_alignbit_b32 v17, v7, v13, v16
	v_cmp_eq_u32_e64 s[50:51], 0, v22
	v_cndmask_b32_e64 v5, v5, v14, s[48:49]
	v_alignbit_b32 v15, v13, v5, v16
	v_cndmask_b32_e64 v7, v17, v7, s[50:51]
	v_cndmask_b32_e32 v4, v12, v4, vcc
	v_cndmask_b32_e64 v13, v15, v13, s[50:51]
	v_bfe_u32 v18, v7, 29, 1
	v_cndmask_b32_e64 v4, v6, v4, s[46:47]
	v_alignbit_b32 v15, v7, v13, 30
	v_sub_u32_e32 v19, 0, v18
	v_cndmask_b32_e64 v4, v14, v4, s[48:49]
	v_xor_b32_e32 v15, v15, v19
	v_alignbit_b32 v6, v5, v4, v16
	v_cndmask_b32_e64 v5, v6, v5, s[50:51]
	v_ffbh_u32_e32 v12, v15
	v_alignbit_b32 v6, v13, v5, 30
	v_min_u32_e32 v12, 32, v12
	v_alignbit_b32 v4, v5, v4, 30
	v_xor_b32_e32 v6, v6, v19
	v_sub_u32_e32 v13, 31, v12
	v_xor_b32_e32 v4, v4, v19
	v_alignbit_b32 v14, v15, v6, v13
	v_alignbit_b32 v4, v6, v4, v13
	v_alignbit_b32 v5, v14, v4, 9
	v_ffbh_u32_e32 v6, v5
	v_min_u32_e32 v6, 32, v6
	v_lshrrev_b32_e32 v17, 29, v7
	v_not_b32_e32 v13, v6
	v_alignbit_b32 v4, v5, v4, v13
	v_lshlrev_b32_e32 v5, 31, v17
	v_or_b32_e32 v13, 0x33000000, v5
	v_add_lshl_u32 v6, v6, v12, 23
	v_lshrrev_b32_e32 v4, 9, v4
	v_sub_u32_e32 v6, v13, v6
	v_or_b32_e32 v5, 0.5, v5
	v_lshlrev_b32_e32 v12, 23, v12
	v_or_b32_e32 v4, v6, v4
	v_lshrrev_b32_e32 v6, 9, v14
	v_sub_u32_e32 v5, v5, v12
	v_or_b32_e32 v5, v6, v5
	v_mul_f32_e32 v6, 0x3fc90fda, v5
	v_fma_f32 v12, v5, s93, -v6
	v_fmac_f32_e32 v12, 0x33a22168, v5
	v_fmac_f32_e32 v12, 0x3fc90fda, v4
	v_lshrrev_b32_e32 v4, 30, v7
	v_add_f32_e32 v12, v6, v12
	v_add_u32_e32 v13, v18, v4
.LBB0_788:
	s_andn2_saveexec_b64 s[14:15], s[14:15]
	v_mul_f32_e64 v4, |v9|, s94
	v_rndne_f32_e32 v4, v4
	v_cvt_i32_f32_e32 v13, v4
	v_fma_f32 v12, v4, s95, |v9|
	v_fmac_f32_e32 v12, 0xb3a22168, v4
	v_fmac_f32_e32 v12, 0xa7c234c4, v4
	s_or_b64 exec, exec, s[14:15]
	s_or_b32 s2, s52, s9
	s_ashr_i32 s3, s2, 31
	v_mov_b32_e32 v4, 0
	s_lshl_b64 s[96:97], s[2:3], 10
	v_mov_b32_e32 v5, v4
	v_mov_b32_e32 v6, v4
	v_mov_b32_e32 v7, v4
	s_waitcnt vmcnt(0)
	v_max_f32_e32 v4, v11, v11
	v_min_f32_e32 v4, 0xb8d1b717, v4
	v_mul_f32_e32 v5, v105, v4
	v_mul_f32_e32 v6, 0x3fb8aa3b, v5
	v_fma_f32 v7, v5, s27, -v6
	v_rndne_f32_e32 v11, v6
	v_fmac_f32_e32 v7, 0x32a5705f, v5
	v_sub_f32_e32 v6, v6, v11
	v_add_f32_e32 v6, v6, v7
	v_exp_f32_e32 v6, v6
	v_cvt_i32_f32_e32 v7, v11
	v_cmp_ngt_f32_e32 vcc, s29, v5
	v_ldexp_f32 v6, v6, v7
	v_and_b32_e32 v7, 1, v13
	v_cndmask_b32_e32 v6, 0, v6, vcc
	v_cmp_nlt_f32_e32 vcc, s10, v5
	v_cmp_eq_u32_e64 s[46:47], 0, v7
	v_mul_f32_e32 v7, v12, v12
	v_cndmask_b32_e32 v5, v223, v6, vcc
	v_cmp_class_f32_e64 vcc, v9, s28
	v_xor_b32_e32 v6, v10, v9
	v_fmamk_f32 v9, v7, 0xb94c1982, v219
	v_fmaak_f32 v9, v7, v9, 0xbe2aaa9d
	v_mul_f32_e32 v9, v7, v9
	v_fmac_f32_e32 v12, v12, v9
	v_fmamk_f32 v9, v7, 0x37d75334, v220
	v_fmaak_f32 v9, v7, v9, 0x3d2aabf7
	v_fmaak_f32 v9, v7, v9, 0xbf000004
	v_fma_f32 v7, v7, v9, 1.0
	v_cndmask_b32_e64 v9, v7, v12, s[46:47]
	v_lshlrev_b32_e32 v10, 30, v13
	v_xor_b32_e32 v6, v6, v9
	v_xor_b32_e32 v9, 0x80000000, v12
	v_and_b32_e32 v11, 0x80000000, v10
	v_cndmask_b32_e64 v7, v9, v7, s[46:47]
	v_xor_b32_e32 v6, v6, v11
	v_bitop3_b32 v7, v7, v10, s33 bitop3:0x78
	v_cndmask_b32_e32 v6, v251, v6, vcc
	v_cndmask_b32_e32 v7, v251, v7, vcc
	v_mul_f32_e32 v6, v5, v6
	v_fma_f32 v10, v5, v7, -1.0
	v_mov_b32_e32 v7, v4
	v_mov_b32_e32 v11, v8
	v_pk_mul_f32 v[12:13], v[4:5], v[6:7] op_sel_hi:[0,1]
	v_pk_mul_f32 v[14:15], v[8:9], v[10:11] op_sel_hi:[0,1]
	v_sub_f32_e32 v5, v12, v14
	v_add_f32_e32 v7, v13, v15
	v_div_scale_f32 v9, s[2:3], v7, v7, v5
	v_rcp_f32_e32 v11, v9
	s_nop 0
	v_fma_f32 v12, -v9, v11, 1.0
	v_fmac_f32_e32 v11, v12, v11
	v_div_scale_f32 v12, vcc, v5, v7, v5
	v_mul_f32_e32 v13, v12, v11
	v_fma_f32 v14, -v9, v13, v12
	v_fmac_f32_e32 v13, v14, v11
	v_fma_f32 v9, -v9, v13, v12
	v_div_fmas_f32 v9, v9, v11, v13
	v_div_fixup_f32 v20, v9, v7, v5
	v_mov_b32_e32 v5, v8
	v_mov_b32_e32 v11, v6
	v_pk_mul_f32 v[4:5], v[4:5], v[10:11]
	s_nop 0
	v_add_f32_e32 v4, v4, v5
	v_div_scale_f32 v5, s[2:3], v7, v7, v4
	v_rcp_f32_e32 v6, v5
	s_nop 0
	v_fma_f32 v8, -v5, v6, 1.0
	v_fmac_f32_e32 v6, v8, v6
	v_div_scale_f32 v8, vcc, v4, v7, v4
	v_mul_f32_e32 v9, v8, v6
	v_fma_f32 v10, -v5, v9, v8
	v_fmac_f32_e32 v9, v10, v6
	v_fma_f32 v5, -v5, v9, v8
	v_div_fmas_f32 v5, v5, v6, v9
	v_div_fixup_f32 v22, v5, v7, v4
	v_lshlrev_b32_e32 v2, 2, v84
	ds_bpermute_b32 v208, v2, v20
	ds_bpermute_b32 v209, v2, v22
	v_add_u32_e32 v201, 32, v2
	ds_bpermute_b32 v210, v201, v20
	ds_bpermute_b32 v211, v201, v22
	v_add_u32_e32 v200, 64, v2
	ds_bpermute_b32 v212, v200, v20
	ds_bpermute_b32 v213, v200, v22
	v_add_u32_e32 v201, 96, v2
	ds_bpermute_b32 v214, v201, v20
	ds_bpermute_b32 v215, v201, v22
	v_add_u32_e32 v200, 128, v2
	ds_bpermute_b32 v216, v200, v20
	ds_bpermute_b32 v217, v200, v22
	v_add_u32_e32 v201, 160, v2
	ds_bpermute_b32 v244, v201, v20
	ds_bpermute_b32 v245, v201, v22
	v_add_u32_e32 v200, 192, v2
	ds_bpermute_b32 v246, v200, v20
	ds_bpermute_b32 v247, v200, v22
	v_add_u32_e32 v201, 224, v2
	ds_bpermute_b32 v248, v201, v20
	ds_bpermute_b32 v249, v201, v22
	s_waitcnt lgkmcnt(0)
	v_mov_b32_e32 v4, 0
	v_mov_b32_e32 v5, 0
	v_mov_b32_e32 v6, 0
	v_mov_b32_e32 v7, 0
	v_mov_b32_e32 v8, 0
	v_mov_b32_e32 v9, 0
	v_mov_b32_e32 v10, 0
	v_mov_b32_e32 v11, 0
	v_mov_b32_e32 v12, 0
	v_mov_b32_e32 v13, 0
	v_mov_b32_e32 v14, 0
	v_mov_b32_e32 v15, 0
	v_mov_b32_e32 v16, 0
	v_mov_b32_e32 v17, 0
	v_mov_b32_e32 v18, 0
	v_mov_b32_e32 v19, 0
	v_mov_b32_e32 v20, 0
	v_mov_b32_e32 v21, 0
	v_mov_b32_e32 v22, 0
	v_mov_b32_e32 v23, 0
	v_mov_b32_e32 v24, 0
	v_mov_b32_e32 v25, 0
	v_mov_b32_e32 v26, 0
	v_mov_b32_e32 v27, 0
	v_mov_b32_e32 v28, 0
	v_mov_b32_e32 v29, 0
	v_mov_b32_e32 v30, 0
	v_mov_b32_e32 v31, 0
	v_mov_b32_e32 v32, 0
	v_mov_b32_e32 v33, 0
	v_mov_b32_e32 v34, 0
	v_mov_b32_e32 v35, 0
	s_and_saveexec_b64 s[0:1], s[40:41]
	s_waitcnt vmcnt(0)
	v_pk_mul_f32 v[196:197], v[208:209], v[146:147] op_sel:[1,0]
	v_pk_mul_f32 v[198:199], v[208:209], v[144:145] op_sel:[1,0]
	v_pk_mul_f32 v[146:147], v[208:209], v[146:147] op_sel_hi:[0,1]
	v_pk_mul_f32 v[144:145], v[208:209], v[144:145] op_sel_hi:[0,1]
	v_pk_fma_f32 v[198:199], v[208:209], v[136:137], v[198:199] op_sel_hi:[0,1,1]
	v_pk_fma_f32 v[196:197], v[208:209], v[138:139], v[196:197] op_sel_hi:[0,1,1]
	v_pk_fma_f32 v[136:137], v[208:209], v[136:137], v[144:145] op_sel:[1,0,0] neg_lo:[0,0,1] neg_hi:[0,0,1]
	v_pk_fma_f32 v[138:139], v[208:209], v[138:139], v[146:147] op_sel:[1,0,0] neg_lo:[0,0,1] neg_hi:[0,0,1]
	v_cndmask_b32_e64 v147, v197, v139, s[44:45]
	v_cndmask_b32_e64 v146, v196, v138, s[44:45]
	v_cndmask_b32_e64 v145, v199, v137, s[44:45]
	v_cndmask_b32_e64 v144, v198, v136, s[44:45]
	v_pk_mul_f32 v[196:197], v[208:209], v[142:143] op_sel:[1,0]
	v_pk_mul_f32 v[198:199], v[208:209], v[140:141] op_sel:[1,0]
	v_pk_mul_f32 v[142:143], v[208:209], v[142:143] op_sel_hi:[0,1]
	v_pk_mul_f32 v[140:141], v[208:209], v[140:141] op_sel_hi:[0,1]
	v_pk_fma_f32 v[198:199], v[208:209], v[132:133], v[198:199] op_sel_hi:[0,1,1]
	v_pk_fma_f32 v[196:197], v[208:209], v[134:135], v[196:197] op_sel_hi:[0,1,1]
	v_pk_fma_f32 v[132:133], v[208:209], v[132:133], v[140:141] op_sel:[1,0,0] neg_lo:[0,0,1] neg_hi:[0,0,1]
	v_pk_fma_f32 v[134:135], v[208:209], v[134:135], v[142:143] op_sel:[1,0,0] neg_lo:[0,0,1] neg_hi:[0,0,1]
	v_cndmask_b32_e64 v143, v197, v135, s[44:45]
	v_cndmask_b32_e64 v142, v196, v134, s[44:45]
	v_cndmask_b32_e64 v141, v199, v133, s[44:45]
	v_cndmask_b32_e64 v140, v198, v132, s[44:45]
	v_cvt_pk_bf16_f32 v4, v144, v145
	v_cvt_pk_bf16_f32 v5, v146, v147
	v_cvt_pk_bf16_f32 v6, v140, v141
	v_cvt_pk_bf16_f32 v7, v142, v143
	v_pk_mul_f32 v[196:197], v[210:211], v[162:163] op_sel:[1,0]
	v_pk_mul_f32 v[198:199], v[210:211], v[160:161] op_sel:[1,0]
	v_pk_mul_f32 v[162:163], v[210:211], v[162:163] op_sel_hi:[0,1]
	v_pk_mul_f32 v[160:161], v[210:211], v[160:161] op_sel_hi:[0,1]
	v_pk_fma_f32 v[198:199], v[210:211], v[152:153], v[198:199] op_sel_hi:[0,1,1]
	v_pk_fma_f32 v[196:197], v[210:211], v[154:155], v[196:197] op_sel_hi:[0,1,1]
	v_pk_fma_f32 v[152:153], v[210:211], v[152:153], v[160:161] op_sel:[1,0,0] neg_lo:[0,0,1] neg_hi:[0,0,1]
	v_pk_fma_f32 v[154:155], v[210:211], v[154:155], v[162:163] op_sel:[1,0,0] neg_lo:[0,0,1] neg_hi:[0,0,1]
	v_cndmask_b32_e64 v163, v197, v155, s[44:45]
	v_cndmask_b32_e64 v162, v196, v154, s[44:45]
	v_cndmask_b32_e64 v161, v199, v153, s[44:45]
	v_cndmask_b32_e64 v160, v198, v152, s[44:45]
	v_pk_mul_f32 v[196:197], v[210:211], v[158:159] op_sel:[1,0]
	v_pk_mul_f32 v[198:199], v[210:211], v[156:157] op_sel:[1,0]
	v_pk_mul_f32 v[158:159], v[210:211], v[158:159] op_sel_hi:[0,1]
	v_pk_mul_f32 v[156:157], v[210:211], v[156:157] op_sel_hi:[0,1]
	v_pk_fma_f32 v[198:199], v[210:211], v[148:149], v[198:199] op_sel_hi:[0,1,1]
	v_pk_fma_f32 v[196:197], v[210:211], v[150:151], v[196:197] op_sel_hi:[0,1,1]
	v_pk_fma_f32 v[148:149], v[210:211], v[148:149], v[156:157] op_sel:[1,0,0] neg_lo:[0,0,1] neg_hi:[0,0,1]
	v_pk_fma_f32 v[150:151], v[210:211], v[150:151], v[158:159] op_sel:[1,0,0] neg_lo:[0,0,1] neg_hi:[0,0,1]
	v_cndmask_b32_e64 v159, v197, v151, s[44:45]
	v_cndmask_b32_e64 v158, v196, v150, s[44:45]
	v_cndmask_b32_e64 v157, v199, v149, s[44:45]
	v_cndmask_b32_e64 v156, v198, v148, s[44:45]
	v_cvt_pk_bf16_f32 v8, v160, v161
	v_cvt_pk_bf16_f32 v9, v162, v163
	v_cvt_pk_bf16_f32 v10, v156, v157
	v_cvt_pk_bf16_f32 v11, v158, v159
	v_pk_mul_f32 v[196:197], v[212:213], v[178:179] op_sel:[1,0]
	v_pk_mul_f32 v[198:199], v[212:213], v[176:177] op_sel:[1,0]
	v_pk_mul_f32 v[178:179], v[212:213], v[178:179] op_sel_hi:[0,1]
	v_pk_mul_f32 v[176:177], v[212:213], v[176:177] op_sel_hi:[0,1]
	v_pk_fma_f32 v[198:199], v[212:213], v[168:169], v[198:199] op_sel_hi:[0,1,1]
	v_pk_fma_f32 v[196:197], v[212:213], v[170:171], v[196:197] op_sel_hi:[0,1,1]
	v_pk_fma_f32 v[168:169], v[212:213], v[168:169], v[176:177] op_sel:[1,0,0] neg_lo:[0,0,1] neg_hi:[0,0,1]
	v_pk_fma_f32 v[170:171], v[212:213], v[170:171], v[178:179] op_sel:[1,0,0] neg_lo:[0,0,1] neg_hi:[0,0,1]
	v_cndmask_b32_e64 v179, v197, v171, s[44:45]
	v_cndmask_b32_e64 v178, v196, v170, s[44:45]
	v_cndmask_b32_e64 v177, v199, v169, s[44:45]
	v_cndmask_b32_e64 v176, v198, v168, s[44:45]
	v_pk_mul_f32 v[196:197], v[212:213], v[174:175] op_sel:[1,0]
	v_pk_mul_f32 v[198:199], v[212:213], v[172:173] op_sel:[1,0]
	v_pk_mul_f32 v[174:175], v[212:213], v[174:175] op_sel_hi:[0,1]
	v_pk_mul_f32 v[172:173], v[212:213], v[172:173] op_sel_hi:[0,1]
	v_pk_fma_f32 v[198:199], v[212:213], v[164:165], v[198:199] op_sel_hi:[0,1,1]
	v_pk_fma_f32 v[196:197], v[212:213], v[166:167], v[196:197] op_sel_hi:[0,1,1]
	v_pk_fma_f32 v[164:165], v[212:213], v[164:165], v[172:173] op_sel:[1,0,0] neg_lo:[0,0,1] neg_hi:[0,0,1]
	v_pk_fma_f32 v[166:167], v[212:213], v[166:167], v[174:175] op_sel:[1,0,0] neg_lo:[0,0,1] neg_hi:[0,0,1]
	v_cndmask_b32_e64 v175, v197, v167, s[44:45]
	v_cndmask_b32_e64 v174, v196, v166, s[44:45]
	v_cndmask_b32_e64 v173, v199, v165, s[44:45]
	v_cndmask_b32_e64 v172, v198, v164, s[44:45]
	v_cvt_pk_bf16_f32 v12, v176, v177
	v_cvt_pk_bf16_f32 v13, v178, v179
	v_cvt_pk_bf16_f32 v14, v172, v173
	v_cvt_pk_bf16_f32 v15, v174, v175
	v_pk_mul_f32 v[196:197], v[214:215], v[194:195] op_sel:[1,0]
	v_pk_mul_f32 v[198:199], v[214:215], v[192:193] op_sel:[1,0]
	v_pk_mul_f32 v[194:195], v[214:215], v[194:195] op_sel_hi:[0,1]
	v_pk_mul_f32 v[192:193], v[214:215], v[192:193] op_sel_hi:[0,1]
	v_pk_fma_f32 v[198:199], v[214:215], v[184:185], v[198:199] op_sel_hi:[0,1,1]
	v_pk_fma_f32 v[196:197], v[214:215], v[186:187], v[196:197] op_sel_hi:[0,1,1]
	v_pk_fma_f32 v[184:185], v[214:215], v[184:185], v[192:193] op_sel:[1,0,0] neg_lo:[0,0,1] neg_hi:[0,0,1]
	v_pk_fma_f32 v[186:187], v[214:215], v[186:187], v[194:195] op_sel:[1,0,0] neg_lo:[0,0,1] neg_hi:[0,0,1]
	v_cndmask_b32_e64 v195, v197, v187, s[44:45]
	v_cndmask_b32_e64 v194, v196, v186, s[44:45]
	v_cndmask_b32_e64 v193, v199, v185, s[44:45]
	v_cndmask_b32_e64 v192, v198, v184, s[44:45]
	v_pk_mul_f32 v[196:197], v[214:215], v[190:191] op_sel:[1,0]
	v_pk_mul_f32 v[198:199], v[214:215], v[188:189] op_sel:[1,0]
	v_pk_mul_f32 v[190:191], v[214:215], v[190:191] op_sel_hi:[0,1]
	v_pk_mul_f32 v[188:189], v[214:215], v[188:189] op_sel_hi:[0,1]
	v_pk_fma_f32 v[198:199], v[214:215], v[180:181], v[198:199] op_sel_hi:[0,1,1]
	v_pk_fma_f32 v[196:197], v[214:215], v[182:183], v[196:197] op_sel_hi:[0,1,1]
	v_pk_fma_f32 v[180:181], v[214:215], v[180:181], v[188:189] op_sel:[1,0,0] neg_lo:[0,0,1] neg_hi:[0,0,1]
	v_pk_fma_f32 v[182:183], v[214:215], v[182:183], v[190:191] op_sel:[1,0,0] neg_lo:[0,0,1] neg_hi:[0,0,1]
	v_cndmask_b32_e64 v191, v197, v183, s[44:45]
	v_cndmask_b32_e64 v190, v196, v182, s[44:45]
	v_cndmask_b32_e64 v189, v199, v181, s[44:45]
	v_cndmask_b32_e64 v188, v198, v180, s[44:45]
	v_cvt_pk_bf16_f32 v16, v192, v193
	v_cvt_pk_bf16_f32 v17, v194, v195
	v_cvt_pk_bf16_f32 v18, v188, v189
	v_cvt_pk_bf16_f32 v19, v190, v191
	v_pk_mul_f32 v[196:197], v[216:217], v[50:51] op_sel:[1,0]
	v_pk_mul_f32 v[198:199], v[216:217], v[48:49] op_sel:[1,0]
	v_pk_mul_f32 v[50:51], v[216:217], v[50:51] op_sel_hi:[0,1]
	v_pk_mul_f32 v[48:49], v[216:217], v[48:49] op_sel_hi:[0,1]
	v_pk_fma_f32 v[198:199], v[216:217], v[40:41], v[198:199] op_sel_hi:[0,1,1]
	v_pk_fma_f32 v[196:197], v[216:217], v[42:43], v[196:197] op_sel_hi:[0,1,1]
	v_pk_fma_f32 v[40:41], v[216:217], v[40:41], v[48:49] op_sel:[1,0,0] neg_lo:[0,0,1] neg_hi:[0,0,1]
	v_pk_fma_f32 v[42:43], v[216:217], v[42:43], v[50:51] op_sel:[1,0,0] neg_lo:[0,0,1] neg_hi:[0,0,1]
	v_cndmask_b32_e64 v51, v197, v43, s[44:45]
	v_cndmask_b32_e64 v50, v196, v42, s[44:45]
	v_cndmask_b32_e64 v49, v199, v41, s[44:45]
	v_cndmask_b32_e64 v48, v198, v40, s[44:45]
	v_pk_mul_f32 v[196:197], v[216:217], v[46:47] op_sel:[1,0]
	v_pk_mul_f32 v[198:199], v[216:217], v[44:45] op_sel:[1,0]
	v_pk_mul_f32 v[46:47], v[216:217], v[46:47] op_sel_hi:[0,1]
	v_pk_mul_f32 v[44:45], v[216:217], v[44:45] op_sel_hi:[0,1]
	v_pk_fma_f32 v[198:199], v[216:217], v[36:37], v[198:199] op_sel_hi:[0,1,1]
	v_pk_fma_f32 v[196:197], v[216:217], v[38:39], v[196:197] op_sel_hi:[0,1,1]
	v_pk_fma_f32 v[36:37], v[216:217], v[36:37], v[44:45] op_sel:[1,0,0] neg_lo:[0,0,1] neg_hi:[0,0,1]
	v_pk_fma_f32 v[38:39], v[216:217], v[38:39], v[46:47] op_sel:[1,0,0] neg_lo:[0,0,1] neg_hi:[0,0,1]
	v_cndmask_b32_e64 v47, v197, v39, s[44:45]
	v_cndmask_b32_e64 v46, v196, v38, s[44:45]
	v_cndmask_b32_e64 v45, v199, v37, s[44:45]
	v_cndmask_b32_e64 v44, v198, v36, s[44:45]
	v_cvt_pk_bf16_f32 v20, v48, v49
	v_cvt_pk_bf16_f32 v21, v50, v51
	v_cvt_pk_bf16_f32 v22, v44, v45
	v_cvt_pk_bf16_f32 v23, v46, v47
	v_pk_mul_f32 v[196:197], v[244:245], v[66:67] op_sel:[1,0]
	v_pk_mul_f32 v[198:199], v[244:245], v[64:65] op_sel:[1,0]
	v_pk_mul_f32 v[66:67], v[244:245], v[66:67] op_sel_hi:[0,1]
	v_pk_mul_f32 v[64:65], v[244:245], v[64:65] op_sel_hi:[0,1]
	v_pk_fma_f32 v[198:199], v[244:245], v[56:57], v[198:199] op_sel_hi:[0,1,1]
	v_pk_fma_f32 v[196:197], v[244:245], v[58:59], v[196:197] op_sel_hi:[0,1,1]
	v_pk_fma_f32 v[56:57], v[244:245], v[56:57], v[64:65] op_sel:[1,0,0] neg_lo:[0,0,1] neg_hi:[0,0,1]
	v_pk_fma_f32 v[58:59], v[244:245], v[58:59], v[66:67] op_sel:[1,0,0] neg_lo:[0,0,1] neg_hi:[0,0,1]
	v_cndmask_b32_e64 v67, v197, v59, s[44:45]
	v_cndmask_b32_e64 v66, v196, v58, s[44:45]
	v_cndmask_b32_e64 v65, v199, v57, s[44:45]
	v_cndmask_b32_e64 v64, v198, v56, s[44:45]
	v_pk_mul_f32 v[196:197], v[244:245], v[62:63] op_sel:[1,0]
	v_pk_mul_f32 v[198:199], v[244:245], v[60:61] op_sel:[1,0]
	v_pk_mul_f32 v[62:63], v[244:245], v[62:63] op_sel_hi:[0,1]
	v_pk_mul_f32 v[60:61], v[244:245], v[60:61] op_sel_hi:[0,1]
	v_pk_fma_f32 v[198:199], v[244:245], v[52:53], v[198:199] op_sel_hi:[0,1,1]
	v_pk_fma_f32 v[196:197], v[244:245], v[54:55], v[196:197] op_sel_hi:[0,1,1]
	v_pk_fma_f32 v[52:53], v[244:245], v[52:53], v[60:61] op_sel:[1,0,0] neg_lo:[0,0,1] neg_hi:[0,0,1]
	v_pk_fma_f32 v[54:55], v[244:245], v[54:55], v[62:63] op_sel:[1,0,0] neg_lo:[0,0,1] neg_hi:[0,0,1]
	v_cndmask_b32_e64 v63, v197, v55, s[44:45]
	v_cndmask_b32_e64 v62, v196, v54, s[44:45]
	v_cndmask_b32_e64 v61, v199, v53, s[44:45]
	v_cndmask_b32_e64 v60, v198, v52, s[44:45]
	v_cvt_pk_bf16_f32 v24, v64, v65
	v_cvt_pk_bf16_f32 v25, v66, v67
	v_cvt_pk_bf16_f32 v26, v60, v61
	v_cvt_pk_bf16_f32 v27, v62, v63
	v_pk_mul_f32 v[196:197], v[246:247], v[82:83] op_sel:[1,0]
	v_pk_mul_f32 v[198:199], v[246:247], v[80:81] op_sel:[1,0]
	v_pk_mul_f32 v[82:83], v[246:247], v[82:83] op_sel_hi:[0,1]
	v_pk_mul_f32 v[80:81], v[246:247], v[80:81] op_sel_hi:[0,1]
	v_pk_fma_f32 v[198:199], v[246:247], v[72:73], v[198:199] op_sel_hi:[0,1,1]
	v_pk_fma_f32 v[196:197], v[246:247], v[74:75], v[196:197] op_sel_hi:[0,1,1]
	v_pk_fma_f32 v[72:73], v[246:247], v[72:73], v[80:81] op_sel:[1,0,0] neg_lo:[0,0,1] neg_hi:[0,0,1]
	v_pk_fma_f32 v[74:75], v[246:247], v[74:75], v[82:83] op_sel:[1,0,0] neg_lo:[0,0,1] neg_hi:[0,0,1]
	v_cndmask_b32_e64 v83, v197, v75, s[44:45]
	v_cndmask_b32_e64 v82, v196, v74, s[44:45]
	v_cndmask_b32_e64 v81, v199, v73, s[44:45]
	v_cndmask_b32_e64 v80, v198, v72, s[44:45]
	v_pk_mul_f32 v[196:197], v[246:247], v[78:79] op_sel:[1,0]
	v_pk_mul_f32 v[198:199], v[246:247], v[76:77] op_sel:[1,0]
	v_pk_mul_f32 v[78:79], v[246:247], v[78:79] op_sel_hi:[0,1]
	v_pk_mul_f32 v[76:77], v[246:247], v[76:77] op_sel_hi:[0,1]
	v_pk_fma_f32 v[198:199], v[246:247], v[68:69], v[198:199] op_sel_hi:[0,1,1]
	v_pk_fma_f32 v[196:197], v[246:247], v[70:71], v[196:197] op_sel_hi:[0,1,1]
	v_pk_fma_f32 v[68:69], v[246:247], v[68:69], v[76:77] op_sel:[1,0,0] neg_lo:[0,0,1] neg_hi:[0,0,1]
	v_pk_fma_f32 v[70:71], v[246:247], v[70:71], v[78:79] op_sel:[1,0,0] neg_lo:[0,0,1] neg_hi:[0,0,1]
	v_cndmask_b32_e64 v79, v197, v71, s[44:45]
	v_cndmask_b32_e64 v78, v196, v70, s[44:45]
	v_cndmask_b32_e64 v77, v199, v69, s[44:45]
	v_cndmask_b32_e64 v76, v198, v68, s[44:45]
	v_cvt_pk_bf16_f32 v28, v80, v81
	v_cvt_pk_bf16_f32 v29, v82, v83
	v_cvt_pk_bf16_f32 v30, v76, v77
	v_cvt_pk_bf16_f32 v31, v78, v79
	v_pk_mul_f32 v[196:197], v[248:249], v[242:243] op_sel:[1,0]
	v_pk_mul_f32 v[198:199], v[248:249], v[240:241] op_sel:[1,0]
	v_pk_mul_f32 v[242:243], v[248:249], v[242:243] op_sel_hi:[0,1]
	v_pk_mul_f32 v[240:241], v[248:249], v[240:241] op_sel_hi:[0,1]
	v_pk_fma_f32 v[198:199], v[248:249], v[232:233], v[198:199] op_sel_hi:[0,1,1]
	v_pk_fma_f32 v[196:197], v[248:249], v[234:235], v[196:197] op_sel_hi:[0,1,1]
	v_pk_fma_f32 v[232:233], v[248:249], v[232:233], v[240:241] op_sel:[1,0,0] neg_lo:[0,0,1] neg_hi:[0,0,1]
	v_pk_fma_f32 v[234:235], v[248:249], v[234:235], v[242:243] op_sel:[1,0,0] neg_lo:[0,0,1] neg_hi:[0,0,1]
	v_cndmask_b32_e64 v243, v197, v235, s[44:45]
	v_cndmask_b32_e64 v242, v196, v234, s[44:45]
	v_cndmask_b32_e64 v241, v199, v233, s[44:45]
	v_cndmask_b32_e64 v240, v198, v232, s[44:45]
	v_pk_mul_f32 v[196:197], v[248:249], v[238:239] op_sel:[1,0]
	v_pk_mul_f32 v[198:199], v[248:249], v[236:237] op_sel:[1,0]
	v_pk_mul_f32 v[238:239], v[248:249], v[238:239] op_sel_hi:[0,1]
	v_pk_mul_f32 v[236:237], v[248:249], v[236:237] op_sel_hi:[0,1]
	v_pk_fma_f32 v[198:199], v[248:249], v[228:229], v[198:199] op_sel_hi:[0,1,1]
	v_pk_fma_f32 v[196:197], v[248:249], v[230:231], v[196:197] op_sel_hi:[0,1,1]
	v_pk_fma_f32 v[228:229], v[248:249], v[228:229], v[236:237] op_sel:[1,0,0] neg_lo:[0,0,1] neg_hi:[0,0,1]
	v_pk_fma_f32 v[230:231], v[248:249], v[230:231], v[238:239] op_sel:[1,0,0] neg_lo:[0,0,1] neg_hi:[0,0,1]
	v_cndmask_b32_e64 v239, v197, v231, s[44:45]
	v_cndmask_b32_e64 v238, v196, v230, s[44:45]
	v_cndmask_b32_e64 v237, v199, v229, s[44:45]
	v_cndmask_b32_e64 v236, v198, v228, s[44:45]
	v_cvt_pk_bf16_f32 v32, v240, v241
	v_cvt_pk_bf16_f32 v33, v242, v243
	v_cvt_pk_bf16_f32 v34, v236, v237
	v_cvt_pk_bf16_f32 v35, v238, v239

.LBB0_851:
	s_lshl_b32 s17, s37, 3
	s_add_i32 s17, s17, s6
	s_bfe_u32 s7, s17, 0x70001
	s_or_b32 s2, s7, s24
	s_ashr_i32 s3, s2, 31
	s_lshl_b64 s[12:13], s[2:3], 8
	s_add_u32 s0, s66, s12
	s_addc_u32 s1, s67, s13
	s_add_u32 s12, s68, s12
	s_addc_u32 s13, s69, s13
	s_lshl_b64 s[2:3], s[2:3], 2
	s_add_u32 s2, s70, s2
	s_addc_u32 s3, s71, s3
	global_load_dword v2, v3, s[2:3]
	s_or_b32 s46, s7, s9
	s_ashr_i32 s47, s46, 31
	s_lshl_b64 s[46:47], s[46:47], 10
	v_mov_b32_e32 v197, s47
	v_or_b32_e32 v196, s46, v92
	v_lshlrev_b64 v[196:197], 2, v[196:197]
	v_lshl_add_u64 v[198:199], v[112:113], 0, v[196:197]
	v_lshl_add_u64 v[200:201], v[114:115], 0, v[196:197]
	s_and_saveexec_b64 s[14:15], s[40:41]
	global_load_dwordx4 v[132:135], v[198:199], off offset:16
	global_load_dwordx4 v[136:139], v[198:199], off
	global_load_dwordx4 v[140:143], v[200:201], off offset:16
	global_load_dwordx4 v[144:147], v[200:201], off
	global_load_dwordx4 v[148:151], v[198:199], off offset:528
	global_load_dwordx4 v[152:155], v[198:199], off offset:512
	global_load_dwordx4 v[156:159], v[200:201], off offset:528
	global_load_dwordx4 v[160:163], v[200:201], off offset:512
	global_load_dwordx4 v[164:167], v[198:199], off offset:1040
	global_load_dwordx4 v[168:171], v[198:199], off offset:1024
	global_load_dwordx4 v[172:175], v[200:201], off offset:1040
	global_load_dwordx4 v[176:179], v[200:201], off offset:1024
	global_load_dwordx4 v[180:183], v[198:199], off offset:1552
	global_load_dwordx4 v[184:187], v[198:199], off offset:1536
	global_load_dwordx4 v[188:191], v[200:201], off offset:1552
	global_load_dwordx4 v[192:195], v[200:201], off offset:1536
	global_load_dwordx4 v[36:39], v[198:199], off offset:2064
	global_load_dwordx4 v[40:43], v[198:199], off offset:2048
	global_load_dwordx4 v[44:47], v[200:201], off offset:2064
	global_load_dwordx4 v[48:51], v[200:201], off offset:2048
	global_load_dwordx4 v[52:55], v[198:199], off offset:2576
	global_load_dwordx4 v[56:59], v[198:199], off offset:2560
	global_load_dwordx4 v[60:63], v[200:201], off offset:2576
	global_load_dwordx4 v[64:67], v[200:201], off offset:2560
	global_load_dwordx4 v[68:71], v[198:199], off offset:3088
	global_load_dwordx4 v[72:75], v[198:199], off offset:3072
	global_load_dwordx4 v[76:79], v[200:201], off offset:3088
	global_load_dwordx4 v[80:83], v[200:201], off offset:3072
	global_load_dwordx4 v[228:231], v[198:199], off offset:3600
	global_load_dwordx4 v[232:235], v[198:199], off offset:3584
	global_load_dwordx4 v[236:239], v[200:201], off offset:3600
	global_load_dwordx4 v[240:243], v[200:201], off offset:3584
	s_mov_b64 exec, s[14:15]
	s_waitcnt vmcnt(32)
	v_mul_f32_e32 v4, 0x3fb8aa3b, v2
	v_fma_f32 v5, v2, s27, -v4
	v_rndne_f32_e32 v6, v4
	v_fmac_f32_e32 v5, 0x32a5705f, v2
	v_sub_f32_e32 v4, v4, v6
	v_add_f32_e32 v4, v4, v5
	v_exp_f32_e32 v4, v4
	v_cvt_i32_f32_e32 v5, v6
	v_cmp_ngt_f32_e32 vcc, s29, v2
	v_ldexp_f32 v4, v4, v5
	s_nop 0
	v_cndmask_b32_e32 v4, 0, v4, vcc
	v_cmp_nlt_f32_e32 vcc, s10, v2
	s_nop 1
	v_cndmask_b32_e32 v103, v223, v4, vcc
	v_lshlrev_b64 v[4:5], 2, v[0:1]
	v_lshl_add_u64 v[6:7], s[0:1], 0, v[4:5]
	v_lshl_add_u64 v[4:5], s[12:13], 0, v[4:5]
	global_load_dword v2, v[4:5], off
	global_load_dword v105, v[6:7], off
	s_waitcnt vmcnt(1)
	v_mul_f32_e32 v107, v103, v2
	v_and_b32_e32 v122, 0x7fffffff, v107
	v_cmp_nlt_f32_e64 s[2:3], |v107|, s11
	s_and_saveexec_b64 s[14:15], s[2:3]
	s_xor_b64 s[14:15], exec, s[14:15]
	s_cbranch_execz .LBB0_853
	v_lshrrev_b32_e32 v2, 23, v122
	v_add_u32_e32 v2, 0xffffff88, v2
	v_cmp_lt_u32_e32 vcc, 63, v2
	s_nop 1
	v_cndmask_b32_e32 v4, 0, v224, vcc
	v_add_u32_e32 v2, v4, v2
	v_cmp_lt_u32_e64 s[46:47], 31, v2
	s_nop 1
	v_cndmask_b32_e64 v4, 0, v250, s[46:47]
	v_add_u32_e32 v2, v4, v2
	v_cmp_lt_u32_e64 s[48:49], 31, v2
	s_nop 1
	v_cndmask_b32_e64 v4, 0, v250, s[48:49]
	v_add_u32_e32 v18, v4, v2
	v_and_b32_e32 v2, 0x7fffff, v122
	v_or_b32_e32 v16, 0x800000, v2
	v_mad_u64_u32 v[4:5], s[2:3], v16, s26, 0
	v_mov_b32_e32 v2, v5
	v_mad_u64_u32 v[6:7], s[2:3], v16, s34, v[2:3]
	v_mov_b32_e32 v2, v7
	v_mad_u64_u32 v[8:9], s[2:3], v16, s88, v[2:3]
	v_mov_b32_e32 v2, v9
	v_mad_u64_u32 v[10:11], s[2:3], v16, s89, v[2:3]
	v_mov_b32_e32 v2, v11
	v_mad_u64_u32 v[12:13], s[2:3], v16, s90, v[2:3]
	v_mov_b32_e32 v2, v13
	v_mad_u64_u32 v[14:15], s[2:3], v16, s91, v[2:3]
	v_mov_b32_e32 v2, v15
	v_mad_u64_u32 v[16:17], s[2:3], v16, s92, v[2:3]
	v_cndmask_b32_e32 v5, v14, v10, vcc
	v_cndmask_b32_e32 v2, v16, v12, vcc
	v_cndmask_b32_e32 v9, v17, v14, vcc
	v_cndmask_b32_e64 v7, v2, v5, s[46:47]
	v_cndmask_b32_e64 v2, v9, v2, s[46:47]
	v_cndmask_b32_e32 v9, v12, v8, vcc
	v_cndmask_b32_e64 v5, v5, v9, s[46:47]
	v_cndmask_b32_e32 v6, v10, v6, vcc
	v_cndmask_b32_e64 v2, v2, v7, s[48:49]
	v_cndmask_b32_e64 v7, v7, v5, s[48:49]
	v_sub_u32_e32 v11, 32, v18
	v_cndmask_b32_e64 v9, v9, v6, s[46:47]
	v_alignbit_b32 v12, v2, v7, v11
	v_cmp_eq_u32_e64 s[50:51], 0, v18
	v_cndmask_b32_e64 v5, v5, v9, s[48:49]
	v_cndmask_b32_e32 v4, v8, v4, vcc
	v_cndmask_b32_e64 v2, v12, v2, s[50:51]
	v_alignbit_b32 v10, v7, v5, v11
	v_cndmask_b32_e64 v4, v6, v4, s[46:47]
	v_cndmask_b32_e64 v7, v10, v7, s[50:51]
	v_bfe_u32 v13, v2, 29, 1
	v_cndmask_b32_e64 v4, v9, v4, s[48:49]
	v_alignbit_b32 v10, v2, v7, 30
	v_sub_u32_e32 v14, 0, v13
	v_alignbit_b32 v6, v5, v4, v11
	v_xor_b32_e32 v10, v10, v14
	v_cndmask_b32_e64 v5, v6, v5, s[50:51]
	v_alignbit_b32 v6, v7, v5, 30
	v_ffbh_u32_e32 v7, v10
	v_min_u32_e32 v7, 32, v7
	v_alignbit_b32 v4, v5, v4, 30
	v_xor_b32_e32 v6, v6, v14
	v_sub_u32_e32 v8, 31, v7
	v_xor_b32_e32 v4, v4, v14
	v_alignbit_b32 v9, v10, v6, v8
	v_alignbit_b32 v4, v6, v4, v8
	v_alignbit_b32 v5, v9, v4, 9
	v_ffbh_u32_e32 v6, v5
	v_min_u32_e32 v6, 32, v6
	v_lshrrev_b32_e32 v12, 29, v2
	v_not_b32_e32 v8, v6
	v_alignbit_b32 v4, v5, v4, v8
	v_lshlrev_b32_e32 v5, 31, v12
	v_or_b32_e32 v8, 0x33000000, v5
	v_add_lshl_u32 v6, v6, v7, 23
	v_lshrrev_b32_e32 v4, 9, v4
	v_sub_u32_e32 v6, v8, v6
	v_or_b32_e32 v5, 0.5, v5
	v_lshlrev_b32_e32 v7, 23, v7
	v_or_b32_e32 v4, v6, v4
	v_lshrrev_b32_e32 v6, 9, v9
	v_sub_u32_e32 v5, v5, v7
	v_or_b32_e32 v5, v6, v5
	v_mul_f32_e32 v6, 0x3fc90fda, v5
	v_fma_f32 v7, v5, s93, -v6
	v_fmac_f32_e32 v7, 0x33a22168, v5
	v_fmac_f32_e32 v7, 0x3fc90fda, v4
	v_lshrrev_b32_e32 v2, 30, v2
	v_add_f32_e32 v123, v6, v7
	v_add_u32_e32 v124, v13, v2
.LBB0_853:
	s_andn2_saveexec_b64 s[14:15], s[14:15]
	v_mul_f32_e64 v2, |v107|, s94
	v_rndne_f32_e32 v2, v2
	v_cvt_i32_f32_e32 v124, v2
	v_fma_f32 v123, v2, s95, |v107|
	v_fmac_f32_e32 v123, 0xb3a22168, v2
	v_fmac_f32_e32 v123, 0xa7c234c4, v2
	s_or_b64 exec, exec, s[14:15]
	v_lshlrev_b32_e32 v2, 2, v0
	global_load_dword v8, v2, s[12:13]
	global_load_dword v11, v2, s[0:1]
	s_waitcnt vmcnt(1)
	v_mul_f32_e32 v9, v103, v8
	v_and_b32_e32 v10, 0x7fffffff, v9
	v_cmp_nlt_f32_e64 s[2:3], |v9|, s11
	s_and_saveexec_b64 s[14:15], s[2:3]
	s_xor_b64 s[14:15], exec, s[14:15]
	s_cbranch_execz .LBB0_857
	v_lshrrev_b32_e32 v4, 23, v10
	v_add_u32_e32 v4, 0xffffff88, v4
	v_cmp_lt_u32_e32 vcc, 63, v4
	v_mov_b32_e32 v7, v3
	v_mov_b32_e32 v13, v3
	v_cndmask_b32_e32 v5, 0, v224, vcc
	v_add_u32_e32 v4, v5, v4
	v_cmp_lt_u32_e64 s[46:47], 31, v4
	v_mov_b32_e32 v15, v3
	v_mov_b32_e32 v17, v3
	v_cndmask_b32_e64 v5, 0, v250, s[46:47]
	v_add_u32_e32 v4, v5, v4
	v_cmp_lt_u32_e64 s[48:49], 31, v4
	v_mov_b32_e32 v19, v3
	v_mov_b32_e32 v21, v3
	v_cndmask_b32_e64 v5, 0, v250, s[48:49]
	v_add_u32_e32 v22, v5, v4
	v_and_b32_e32 v4, 0x7fffff, v10
	v_or_b32_e32 v23, 0x800000, v4
	v_mad_u64_u32 v[4:5], s[2:3], v23, s26, 0
	v_mov_b32_e32 v6, v5
	v_mad_u64_u32 v[6:7], s[2:3], v23, s34, v[6:7]
	v_mov_b32_e32 v12, v7
	v_mad_u64_u32 v[12:13], s[2:3], v23, s88, v[12:13]
	v_mov_b32_e32 v14, v13
	v_mad_u64_u32 v[14:15], s[2:3], v23, s89, v[14:15]
	v_mov_b32_e32 v16, v15
	v_mad_u64_u32 v[16:17], s[2:3], v23, s90, v[16:17]
	v_mov_b32_e32 v18, v17
	v_mad_u64_u32 v[18:19], s[2:3], v23, s91, v[18:19]
	v_mov_b32_e32 v20, v19
	v_mad_u64_u32 v[20:21], s[2:3], v23, s92, v[20:21]
	v_cndmask_b32_e32 v5, v18, v14, vcc
	v_cndmask_b32_e32 v7, v20, v16, vcc
	v_cndmask_b32_e32 v15, v21, v18, vcc
	v_cndmask_b32_e64 v13, v7, v5, s[46:47]
	v_cndmask_b32_e64 v7, v15, v7, s[46:47]
	v_cndmask_b32_e32 v15, v16, v12, vcc
	v_cndmask_b32_e64 v5, v5, v15, s[46:47]
	v_cndmask_b32_e32 v6, v14, v6, vcc
	v_cndmask_b32_e64 v7, v7, v13, s[48:49]
	v_cndmask_b32_e64 v13, v13, v5, s[48:49]
	v_sub_u32_e32 v16, 32, v22
	v_cndmask_b32_e64 v14, v15, v6, s[46:47]
	v_alignbit_b32 v17, v7, v13, v16
	v_cmp_eq_u32_e64 s[50:51], 0, v22
	v_cndmask_b32_e64 v5, v5, v14, s[48:49]
	v_alignbit_b32 v15, v13, v5, v16
	v_cndmask_b32_e64 v7, v17, v7, s[50:51]
	v_cndmask_b32_e32 v4, v12, v4, vcc
	v_cndmask_b32_e64 v13, v15, v13, s[50:51]
	v_bfe_u32 v18, v7, 29, 1
	v_cndmask_b32_e64 v4, v6, v4, s[46:47]
	v_alignbit_b32 v15, v7, v13, 30
	v_sub_u32_e32 v19, 0, v18
	v_cndmask_b32_e64 v4, v14, v4, s[48:49]
	v_xor_b32_e32 v15, v15, v19
	v_alignbit_b32 v6, v5, v4, v16
	v_cndmask_b32_e64 v5, v6, v5, s[50:51]
	v_ffbh_u32_e32 v12, v15
	v_alignbit_b32 v6, v13, v5, 30
	v_min_u32_e32 v12, 32, v12
	v_alignbit_b32 v4, v5, v4, 30
	v_xor_b32_e32 v6, v6, v19
	v_sub_u32_e32 v13, 31, v12
	v_xor_b32_e32 v4, v4, v19
	v_alignbit_b32 v14, v15, v6, v13
	v_alignbit_b32 v4, v6, v4, v13
	v_alignbit_b32 v5, v14, v4, 9
	v_ffbh_u32_e32 v6, v5
	v_min_u32_e32 v6, 32, v6
	v_lshrrev_b32_e32 v17, 29, v7
	v_not_b32_e32 v13, v6
	v_alignbit_b32 v4, v5, v4, v13
	v_lshlrev_b32_e32 v5, 31, v17
	v_or_b32_e32 v13, 0x33000000, v5
	v_add_lshl_u32 v6, v6, v12, 23
	v_lshrrev_b32_e32 v4, 9, v4
	v_sub_u32_e32 v6, v13, v6
	v_or_b32_e32 v5, 0.5, v5
	v_lshlrev_b32_e32 v12, 23, v12
	v_or_b32_e32 v4, v6, v4
	v_lshrrev_b32_e32 v6, 9, v14
	v_sub_u32_e32 v5, v5, v12
	v_or_b32_e32 v5, v6, v5
	v_mul_f32_e32 v6, 0x3fc90fda, v5
	v_fma_f32 v12, v5, s93, -v6
	v_fmac_f32_e32 v12, 0x33a22168, v5
	v_fmac_f32_e32 v12, 0x3fc90fda, v4
	v_lshrrev_b32_e32 v4, 30, v7
	v_add_f32_e32 v12, v6, v12
	v_add_u32_e32 v13, v18, v4
.LBB0_857:
	s_andn2_saveexec_b64 s[14:15], s[14:15]
	v_mul_f32_e64 v4, |v9|, s94
	v_rndne_f32_e32 v4, v4
	v_cvt_i32_f32_e32 v13, v4
	v_fma_f32 v12, v4, s95, |v9|
	v_fmac_f32_e32 v12, 0xb3a22168, v4
	v_fmac_f32_e32 v12, 0xa7c234c4, v4
	s_or_b64 exec, exec, s[14:15]
	s_or_b32 s2, s7, s9
	s_ashr_i32 s3, s2, 31
	v_mov_b32_e32 v4, 0
	s_lshl_b64 s[58:59], s[2:3], 10
	v_mov_b32_e32 v5, v4
	v_mov_b32_e32 v6, v4
	v_mov_b32_e32 v7, v4
	s_waitcnt vmcnt(0)
	v_max_f32_e32 v4, v11, v11
	v_min_f32_e32 v4, 0xb8d1b717, v4
	v_mul_f32_e32 v5, v103, v4
	v_mul_f32_e32 v6, 0x3fb8aa3b, v5
	v_fma_f32 v7, v5, s27, -v6
	v_rndne_f32_e32 v11, v6
	v_fmac_f32_e32 v7, 0x32a5705f, v5
	v_sub_f32_e32 v6, v6, v11
	v_add_f32_e32 v6, v6, v7
	v_exp_f32_e32 v6, v6
	v_cvt_i32_f32_e32 v7, v11
	v_cmp_ngt_f32_e32 vcc, s29, v5
	v_ldexp_f32 v6, v6, v7
	v_and_b32_e32 v7, 1, v13
	v_cndmask_b32_e32 v6, 0, v6, vcc
	v_cmp_nlt_f32_e32 vcc, s10, v5
	v_cmp_eq_u32_e64 s[46:47], 0, v7
	v_mul_f32_e32 v7, v12, v12
	v_cndmask_b32_e32 v5, v223, v6, vcc
	v_cmp_class_f32_e64 vcc, v9, s28
	v_xor_b32_e32 v6, v10, v9
	v_fmamk_f32 v9, v7, 0xb94c1982, v219
	v_fmaak_f32 v9, v7, v9, 0xbe2aaa9d
	v_mul_f32_e32 v9, v7, v9
	v_fmac_f32_e32 v12, v12, v9
	v_fmamk_f32 v9, v7, 0x37d75334, v220
	v_fmaak_f32 v9, v7, v9, 0x3d2aabf7
	v_fmaak_f32 v9, v7, v9, 0xbf000004
	v_fma_f32 v7, v7, v9, 1.0
	v_cndmask_b32_e64 v9, v7, v12, s[46:47]
	v_lshlrev_b32_e32 v10, 30, v13
	v_xor_b32_e32 v6, v6, v9
	v_xor_b32_e32 v9, 0x80000000, v12
	v_and_b32_e32 v11, 0x80000000, v10
	v_cndmask_b32_e64 v7, v9, v7, s[46:47]
	v_xor_b32_e32 v6, v6, v11
	v_bitop3_b32 v7, v7, v10, s33 bitop3:0x78
	v_cndmask_b32_e32 v6, v251, v6, vcc
	v_cndmask_b32_e32 v7, v251, v7, vcc
	v_mul_f32_e32 v6, v5, v6
	v_fma_f32 v10, v5, v7, -1.0
	v_mov_b32_e32 v7, v4
	v_mov_b32_e32 v11, v8
	v_pk_mul_f32 v[12:13], v[4:5], v[6:7] op_sel_hi:[0,1]
	v_pk_mul_f32 v[14:15], v[8:9], v[10:11] op_sel_hi:[0,1]
	v_sub_f32_e32 v5, v12, v14
	v_add_f32_e32 v7, v13, v15
	v_div_scale_f32 v9, s[2:3], v7, v7, v5
	v_rcp_f32_e32 v11, v9
	s_nop 0
	v_fma_f32 v12, -v9, v11, 1.0
	v_fmac_f32_e32 v11, v12, v11
	v_div_scale_f32 v12, vcc, v5, v7, v5
	v_mul_f32_e32 v13, v12, v11
	v_fma_f32 v14, -v9, v13, v12
	v_fmac_f32_e32 v13, v14, v11
	v_fma_f32 v9, -v9, v13, v12
	v_div_fmas_f32 v9, v9, v11, v13
	v_div_fixup_f32 v20, v9, v7, v5
	v_mov_b32_e32 v5, v8
	v_mov_b32_e32 v11, v6
	v_pk_mul_f32 v[4:5], v[4:5], v[10:11]
	s_nop 0
	v_add_f32_e32 v4, v4, v5
	v_div_scale_f32 v5, s[2:3], v7, v7, v4
	v_rcp_f32_e32 v6, v5
	s_nop 0
	v_fma_f32 v8, -v5, v6, 1.0
	v_fmac_f32_e32 v6, v8, v6
	v_div_scale_f32 v8, vcc, v4, v7, v4
	v_mul_f32_e32 v9, v8, v6
	v_fma_f32 v10, -v5, v9, v8
	v_fmac_f32_e32 v9, v10, v6
	v_fma_f32 v5, -v5, v9, v8
	v_div_fmas_f32 v5, v5, v6, v9
	v_div_fixup_f32 v22, v5, v7, v4
	v_lshlrev_b32_e32 v2, 2, v84
	ds_bpermute_b32 v208, v2, v20
	ds_bpermute_b32 v209, v2, v22
	v_add_u32_e32 v201, 32, v2
	ds_bpermute_b32 v210, v201, v20
	ds_bpermute_b32 v211, v201, v22
	v_add_u32_e32 v200, 64, v2
	ds_bpermute_b32 v212, v200, v20
	ds_bpermute_b32 v213, v200, v22
	v_add_u32_e32 v201, 96, v2
	ds_bpermute_b32 v214, v201, v20
	ds_bpermute_b32 v215, v201, v22
	v_add_u32_e32 v200, 128, v2
	ds_bpermute_b32 v216, v200, v20
	ds_bpermute_b32 v217, v200, v22
	v_add_u32_e32 v201, 160, v2
	ds_bpermute_b32 v244, v201, v20
	ds_bpermute_b32 v245, v201, v22
	v_add_u32_e32 v200, 192, v2
	ds_bpermute_b32 v246, v200, v20
	ds_bpermute_b32 v247, v200, v22
	v_add_u32_e32 v201, 224, v2
	ds_bpermute_b32 v248, v201, v20
	ds_bpermute_b32 v249, v201, v22
	s_waitcnt lgkmcnt(0)
	v_mov_b32_e32 v4, 0
	v_mov_b32_e32 v5, 0
	v_mov_b32_e32 v6, 0
	v_mov_b32_e32 v7, 0
	v_mov_b32_e32 v8, 0
	v_mov_b32_e32 v9, 0
	v_mov_b32_e32 v10, 0
	v_mov_b32_e32 v11, 0
	v_mov_b32_e32 v12, 0
	v_mov_b32_e32 v13, 0
	v_mov_b32_e32 v14, 0
	v_mov_b32_e32 v15, 0
	v_mov_b32_e32 v16, 0
	v_mov_b32_e32 v17, 0
	v_mov_b32_e32 v18, 0
	v_mov_b32_e32 v19, 0
	v_mov_b32_e32 v20, 0
	v_mov_b32_e32 v21, 0
	v_mov_b32_e32 v22, 0
	v_mov_b32_e32 v23, 0
	v_mov_b32_e32 v24, 0
	v_mov_b32_e32 v25, 0
	v_mov_b32_e32 v26, 0
	v_mov_b32_e32 v27, 0
	v_mov_b32_e32 v28, 0
	v_mov_b32_e32 v29, 0
	v_mov_b32_e32 v30, 0
	v_mov_b32_e32 v31, 0
	v_mov_b32_e32 v32, 0
	v_mov_b32_e32 v33, 0
	v_mov_b32_e32 v34, 0
	v_mov_b32_e32 v35, 0
	s_and_saveexec_b64 s[0:1], s[40:41]
	s_waitcnt vmcnt(0)
	v_pk_mul_f32 v[196:197], v[208:209], v[146:147] op_sel:[1,0]
	v_pk_mul_f32 v[198:199], v[208:209], v[144:145] op_sel:[1,0]
	v_pk_mul_f32 v[146:147], v[208:209], v[146:147] op_sel_hi:[0,1]
	v_pk_mul_f32 v[144:145], v[208:209], v[144:145] op_sel_hi:[0,1]
	v_pk_fma_f32 v[198:199], v[208:209], v[136:137], v[198:199] op_sel_hi:[0,1,1]
	v_pk_fma_f32 v[196:197], v[208:209], v[138:139], v[196:197] op_sel_hi:[0,1,1]
	v_pk_fma_f32 v[136:137], v[208:209], v[136:137], v[144:145] op_sel:[1,0,0] neg_lo:[0,0,1] neg_hi:[0,0,1]
	v_pk_fma_f32 v[138:139], v[208:209], v[138:139], v[146:147] op_sel:[1,0,0] neg_lo:[0,0,1] neg_hi:[0,0,1]
	v_cndmask_b32_e64 v147, v197, v139, s[44:45]
	v_cndmask_b32_e64 v146, v196, v138, s[44:45]
	v_cndmask_b32_e64 v145, v199, v137, s[44:45]
	v_cndmask_b32_e64 v144, v198, v136, s[44:45]
	v_pk_mul_f32 v[196:197], v[208:209], v[142:143] op_sel:[1,0]
	v_pk_mul_f32 v[198:199], v[208:209], v[140:141] op_sel:[1,0]
	v_pk_mul_f32 v[142:143], v[208:209], v[142:143] op_sel_hi:[0,1]
	v_pk_mul_f32 v[140:141], v[208:209], v[140:141] op_sel_hi:[0,1]
	v_pk_fma_f32 v[198:199], v[208:209], v[132:133], v[198:199] op_sel_hi:[0,1,1]
	v_pk_fma_f32 v[196:197], v[208:209], v[134:135], v[196:197] op_sel_hi:[0,1,1]
	v_pk_fma_f32 v[132:133], v[208:209], v[132:133], v[140:141] op_sel:[1,0,0] neg_lo:[0,0,1] neg_hi:[0,0,1]
	v_pk_fma_f32 v[134:135], v[208:209], v[134:135], v[142:143] op_sel:[1,0,0] neg_lo:[0,0,1] neg_hi:[0,0,1]
	v_cndmask_b32_e64 v143, v197, v135, s[44:45]
	v_cndmask_b32_e64 v142, v196, v134, s[44:45]
	v_cndmask_b32_e64 v141, v199, v133, s[44:45]
	v_cndmask_b32_e64 v140, v198, v132, s[44:45]
	v_cvt_pk_bf16_f32 v4, v144, v145
	v_cvt_pk_bf16_f32 v5, v146, v147
	v_cvt_pk_bf16_f32 v6, v140, v141
	v_cvt_pk_bf16_f32 v7, v142, v143
	v_pk_mul_f32 v[196:197], v[210:211], v[162:163] op_sel:[1,0]
	v_pk_mul_f32 v[198:199], v[210:211], v[160:161] op_sel:[1,0]
	v_pk_mul_f32 v[162:163], v[210:211], v[162:163] op_sel_hi:[0,1]
	v_pk_mul_f32 v[160:161], v[210:211], v[160:161] op_sel_hi:[0,1]
	v_pk_fma_f32 v[198:199], v[210:211], v[152:153], v[198:199] op_sel_hi:[0,1,1]
	v_pk_fma_f32 v[196:197], v[210:211], v[154:155], v[196:197] op_sel_hi:[0,1,1]
	v_pk_fma_f32 v[152:153], v[210:211], v[152:153], v[160:161] op_sel:[1,0,0] neg_lo:[0,0,1] neg_hi:[0,0,1]
	v_pk_fma_f32 v[154:155], v[210:211], v[154:155], v[162:163] op_sel:[1,0,0] neg_lo:[0,0,1] neg_hi:[0,0,1]
	v_cndmask_b32_e64 v163, v197, v155, s[44:45]
	v_cndmask_b32_e64 v162, v196, v154, s[44:45]
	v_cndmask_b32_e64 v161, v199, v153, s[44:45]
	v_cndmask_b32_e64 v160, v198, v152, s[44:45]
	v_pk_mul_f32 v[196:197], v[210:211], v[158:159] op_sel:[1,0]
	v_pk_mul_f32 v[198:199], v[210:211], v[156:157] op_sel:[1,0]
	v_pk_mul_f32 v[158:159], v[210:211], v[158:159] op_sel_hi:[0,1]
	v_pk_mul_f32 v[156:157], v[210:211], v[156:157] op_sel_hi:[0,1]
	v_pk_fma_f32 v[198:199], v[210:211], v[148:149], v[198:199] op_sel_hi:[0,1,1]
	v_pk_fma_f32 v[196:197], v[210:211], v[150:151], v[196:197] op_sel_hi:[0,1,1]
	v_pk_fma_f32 v[148:149], v[210:211], v[148:149], v[156:157] op_sel:[1,0,0] neg_lo:[0,0,1] neg_hi:[0,0,1]
	v_pk_fma_f32 v[150:151], v[210:211], v[150:151], v[158:159] op_sel:[1,0,0] neg_lo:[0,0,1] neg_hi:[0,0,1]
	v_cndmask_b32_e64 v159, v197, v151, s[44:45]
	v_cndmask_b32_e64 v158, v196, v150, s[44:45]
	v_cndmask_b32_e64 v157, v199, v149, s[44:45]
	v_cndmask_b32_e64 v156, v198, v148, s[44:45]
	v_cvt_pk_bf16_f32 v8, v160, v161
	v_cvt_pk_bf16_f32 v9, v162, v163
	v_cvt_pk_bf16_f32 v10, v156, v157
	v_cvt_pk_bf16_f32 v11, v158, v159
	v_pk_mul_f32 v[196:197], v[212:213], v[178:179] op_sel:[1,0]
	v_pk_mul_f32 v[198:199], v[212:213], v[176:177] op_sel:[1,0]
	v_pk_mul_f32 v[178:179], v[212:213], v[178:179] op_sel_hi:[0,1]
	v_pk_mul_f32 v[176:177], v[212:213], v[176:177] op_sel_hi:[0,1]
	v_pk_fma_f32 v[198:199], v[212:213], v[168:169], v[198:199] op_sel_hi:[0,1,1]
	v_pk_fma_f32 v[196:197], v[212:213], v[170:171], v[196:197] op_sel_hi:[0,1,1]
	v_pk_fma_f32 v[168:169], v[212:213], v[168:169], v[176:177] op_sel:[1,0,0] neg_lo:[0,0,1] neg_hi:[0,0,1]
	v_pk_fma_f32 v[170:171], v[212:213], v[170:171], v[178:179] op_sel:[1,0,0] neg_lo:[0,0,1] neg_hi:[0,0,1]
	v_cndmask_b32_e64 v179, v197, v171, s[44:45]
	v_cndmask_b32_e64 v178, v196, v170, s[44:45]
	v_cndmask_b32_e64 v177, v199, v169, s[44:45]
	v_cndmask_b32_e64 v176, v198, v168, s[44:45]
	v_pk_mul_f32 v[196:197], v[212:213], v[174:175] op_sel:[1,0]
	v_pk_mul_f32 v[198:199], v[212:213], v[172:173] op_sel:[1,0]
	v_pk_mul_f32 v[174:175], v[212:213], v[174:175] op_sel_hi:[0,1]
	v_pk_mul_f32 v[172:173], v[212:213], v[172:173] op_sel_hi:[0,1]
	v_pk_fma_f32 v[198:199], v[212:213], v[164:165], v[198:199] op_sel_hi:[0,1,1]
	v_pk_fma_f32 v[196:197], v[212:213], v[166:167], v[196:197] op_sel_hi:[0,1,1]
	v_pk_fma_f32 v[164:165], v[212:213], v[164:165], v[172:173] op_sel:[1,0,0] neg_lo:[0,0,1] neg_hi:[0,0,1]
	v_pk_fma_f32 v[166:167], v[212:213], v[166:167], v[174:175] op_sel:[1,0,0] neg_lo:[0,0,1] neg_hi:[0,0,1]
	v_cndmask_b32_e64 v175, v197, v167, s[44:45]
	v_cndmask_b32_e64 v174, v196, v166, s[44:45]
	v_cndmask_b32_e64 v173, v199, v165, s[44:45]
	v_cndmask_b32_e64 v172, v198, v164, s[44:45]
	v_cvt_pk_bf16_f32 v12, v176, v177
	v_cvt_pk_bf16_f32 v13, v178, v179
	v_cvt_pk_bf16_f32 v14, v172, v173
	v_cvt_pk_bf16_f32 v15, v174, v175
	v_pk_mul_f32 v[196:197], v[214:215], v[194:195] op_sel:[1,0]
	v_pk_mul_f32 v[198:199], v[214:215], v[192:193] op_sel:[1,0]
	v_pk_mul_f32 v[194:195], v[214:215], v[194:195] op_sel_hi:[0,1]
	v_pk_mul_f32 v[192:193], v[214:215], v[192:193] op_sel_hi:[0,1]
	v_pk_fma_f32 v[198:199], v[214:215], v[184:185], v[198:199] op_sel_hi:[0,1,1]
	v_pk_fma_f32 v[196:197], v[214:215], v[186:187], v[196:197] op_sel_hi:[0,1,1]
	v_pk_fma_f32 v[184:185], v[214:215], v[184:185], v[192:193] op_sel:[1,0,0] neg_lo:[0,0,1] neg_hi:[0,0,1]
	v_pk_fma_f32 v[186:187], v[214:215], v[186:187], v[194:195] op_sel:[1,0,0] neg_lo:[0,0,1] neg_hi:[0,0,1]
	v_cndmask_b32_e64 v195, v197, v187, s[44:45]
	v_cndmask_b32_e64 v194, v196, v186, s[44:45]
	v_cndmask_b32_e64 v193, v199, v185, s[44:45]
	v_cndmask_b32_e64 v192, v198, v184, s[44:45]
	v_pk_mul_f32 v[196:197], v[214:215], v[190:191] op_sel:[1,0]
	v_pk_mul_f32 v[198:199], v[214:215], v[188:189] op_sel:[1,0]
	v_pk_mul_f32 v[190:191], v[214:215], v[190:191] op_sel_hi:[0,1]
	v_pk_mul_f32 v[188:189], v[214:215], v[188:189] op_sel_hi:[0,1]
	v_pk_fma_f32 v[198:199], v[214:215], v[180:181], v[198:199] op_sel_hi:[0,1,1]
	v_pk_fma_f32 v[196:197], v[214:215], v[182:183], v[196:197] op_sel_hi:[0,1,1]
	v_pk_fma_f32 v[180:181], v[214:215], v[180:181], v[188:189] op_sel:[1,0,0] neg_lo:[0,0,1] neg_hi:[0,0,1]
	v_pk_fma_f32 v[182:183], v[214:215], v[182:183], v[190:191] op_sel:[1,0,0] neg_lo:[0,0,1] neg_hi:[0,0,1]
	v_cndmask_b32_e64 v191, v197, v183, s[44:45]
	v_cndmask_b32_e64 v190, v196, v182, s[44:45]
	v_cndmask_b32_e64 v189, v199, v181, s[44:45]
	v_cndmask_b32_e64 v188, v198, v180, s[44:45]
	v_cvt_pk_bf16_f32 v16, v192, v193
	v_cvt_pk_bf16_f32 v17, v194, v195
	v_cvt_pk_bf16_f32 v18, v188, v189
	v_cvt_pk_bf16_f32 v19, v190, v191
	v_pk_mul_f32 v[196:197], v[216:217], v[50:51] op_sel:[1,0]
	v_pk_mul_f32 v[198:199], v[216:217], v[48:49] op_sel:[1,0]
	v_pk_mul_f32 v[50:51], v[216:217], v[50:51] op_sel_hi:[0,1]
	v_pk_mul_f32 v[48:49], v[216:217], v[48:49] op_sel_hi:[0,1]
	v_pk_fma_f32 v[198:199], v[216:217], v[40:41], v[198:199] op_sel_hi:[0,1,1]
	v_pk_fma_f32 v[196:197], v[216:217], v[42:43], v[196:197] op_sel_hi:[0,1,1]
	v_pk_fma_f32 v[40:41], v[216:217], v[40:41], v[48:49] op_sel:[1,0,0] neg_lo:[0,0,1] neg_hi:[0,0,1]
	v_pk_fma_f32 v[42:43], v[216:217], v[42:43], v[50:51] op_sel:[1,0,0] neg_lo:[0,0,1] neg_hi:[0,0,1]
	v_cndmask_b32_e64 v51, v197, v43, s[44:45]
	v_cndmask_b32_e64 v50, v196, v42, s[44:45]
	v_cndmask_b32_e64 v49, v199, v41, s[44:45]
	v_cndmask_b32_e64 v48, v198, v40, s[44:45]
	v_pk_mul_f32 v[196:197], v[216:217], v[46:47] op_sel:[1,0]
	v_pk_mul_f32 v[198:199], v[216:217], v[44:45] op_sel:[1,0]
	v_pk_mul_f32 v[46:47], v[216:217], v[46:47] op_sel_hi:[0,1]
	v_pk_mul_f32 v[44:45], v[216:217], v[44:45] op_sel_hi:[0,1]
	v_pk_fma_f32 v[198:199], v[216:217], v[36:37], v[198:199] op_sel_hi:[0,1,1]
	v_pk_fma_f32 v[196:197], v[216:217], v[38:39], v[196:197] op_sel_hi:[0,1,1]
	v_pk_fma_f32 v[36:37], v[216:217], v[36:37], v[44:45] op_sel:[1,0,0] neg_lo:[0,0,1] neg_hi:[0,0,1]
	v_pk_fma_f32 v[38:39], v[216:217], v[38:39], v[46:47] op_sel:[1,0,0] neg_lo:[0,0,1] neg_hi:[0,0,1]
	v_cndmask_b32_e64 v47, v197, v39, s[44:45]
	v_cndmask_b32_e64 v46, v196, v38, s[44:45]
	v_cndmask_b32_e64 v45, v199, v37, s[44:45]
	v_cndmask_b32_e64 v44, v198, v36, s[44:45]
	v_cvt_pk_bf16_f32 v20, v48, v49
	v_cvt_pk_bf16_f32 v21, v50, v51
	v_cvt_pk_bf16_f32 v22, v44, v45
	v_cvt_pk_bf16_f32 v23, v46, v47
	v_pk_mul_f32 v[196:197], v[244:245], v[66:67] op_sel:[1,0]
	v_pk_mul_f32 v[198:199], v[244:245], v[64:65] op_sel:[1,0]
	v_pk_mul_f32 v[66:67], v[244:245], v[66:67] op_sel_hi:[0,1]
	v_pk_mul_f32 v[64:65], v[244:245], v[64:65] op_sel_hi:[0,1]
	v_pk_fma_f32 v[198:199], v[244:245], v[56:57], v[198:199] op_sel_hi:[0,1,1]
	v_pk_fma_f32 v[196:197], v[244:245], v[58:59], v[196:197] op_sel_hi:[0,1,1]
	v_pk_fma_f32 v[56:57], v[244:245], v[56:57], v[64:65] op_sel:[1,0,0] neg_lo:[0,0,1] neg_hi:[0,0,1]
	v_pk_fma_f32 v[58:59], v[244:245], v[58:59], v[66:67] op_sel:[1,0,0] neg_lo:[0,0,1] neg_hi:[0,0,1]
	v_cndmask_b32_e64 v67, v197, v59, s[44:45]
	v_cndmask_b32_e64 v66, v196, v58, s[44:45]
	v_cndmask_b32_e64 v65, v199, v57, s[44:45]
	v_cndmask_b32_e64 v64, v198, v56, s[44:45]
	v_pk_mul_f32 v[196:197], v[244:245], v[62:63] op_sel:[1,0]
	v_pk_mul_f32 v[198:199], v[244:245], v[60:61] op_sel:[1,0]
	v_pk_mul_f32 v[62:63], v[244:245], v[62:63] op_sel_hi:[0,1]
	v_pk_mul_f32 v[60:61], v[244:245], v[60:61] op_sel_hi:[0,1]
	v_pk_fma_f32 v[198:199], v[244:245], v[52:53], v[198:199] op_sel_hi:[0,1,1]
	v_pk_fma_f32 v[196:197], v[244:245], v[54:55], v[196:197] op_sel_hi:[0,1,1]
	v_pk_fma_f32 v[52:53], v[244:245], v[52:53], v[60:61] op_sel:[1,0,0] neg_lo:[0,0,1] neg_hi:[0,0,1]
	v_pk_fma_f32 v[54:55], v[244:245], v[54:55], v[62:63] op_sel:[1,0,0] neg_lo:[0,0,1] neg_hi:[0,0,1]
	v_cndmask_b32_e64 v63, v197, v55, s[44:45]
	v_cndmask_b32_e64 v62, v196, v54, s[44:45]
	v_cndmask_b32_e64 v61, v199, v53, s[44:45]
	v_cndmask_b32_e64 v60, v198, v52, s[44:45]
	v_cvt_pk_bf16_f32 v24, v64, v65
	v_cvt_pk_bf16_f32 v25, v66, v67
	v_cvt_pk_bf16_f32 v26, v60, v61
	v_cvt_pk_bf16_f32 v27, v62, v63
	v_pk_mul_f32 v[196:197], v[246:247], v[82:83] op_sel:[1,0]
	v_pk_mul_f32 v[198:199], v[246:247], v[80:81] op_sel:[1,0]
	v_pk_mul_f32 v[82:83], v[246:247], v[82:83] op_sel_hi:[0,1]
	v_pk_mul_f32 v[80:81], v[246:247], v[80:81] op_sel_hi:[0,1]
	v_pk_fma_f32 v[198:199], v[246:247], v[72:73], v[198:199] op_sel_hi:[0,1,1]
	v_pk_fma_f32 v[196:197], v[246:247], v[74:75], v[196:197] op_sel_hi:[0,1,1]
	v_pk_fma_f32 v[72:73], v[246:247], v[72:73], v[80:81] op_sel:[1,0,0] neg_lo:[0,0,1] neg_hi:[0,0,1]
	v_pk_fma_f32 v[74:75], v[246:247], v[74:75], v[82:83] op_sel:[1,0,0] neg_lo:[0,0,1] neg_hi:[0,0,1]
	v_cndmask_b32_e64 v83, v197, v75, s[44:45]
	v_cndmask_b32_e64 v82, v196, v74, s[44:45]
	v_cndmask_b32_e64 v81, v199, v73, s[44:45]
	v_cndmask_b32_e64 v80, v198, v72, s[44:45]
	v_pk_mul_f32 v[196:197], v[246:247], v[78:79] op_sel:[1,0]
	v_pk_mul_f32 v[198:199], v[246:247], v[76:77] op_sel:[1,0]
	v_pk_mul_f32 v[78:79], v[246:247], v[78:79] op_sel_hi:[0,1]
	v_pk_mul_f32 v[76:77], v[246:247], v[76:77] op_sel_hi:[0,1]
	v_pk_fma_f32 v[198:199], v[246:247], v[68:69], v[198:199] op_sel_hi:[0,1,1]
	v_pk_fma_f32 v[196:197], v[246:247], v[70:71], v[196:197] op_sel_hi:[0,1,1]
	v_pk_fma_f32 v[68:69], v[246:247], v[68:69], v[76:77] op_sel:[1,0,0] neg_lo:[0,0,1] neg_hi:[0,0,1]
	v_pk_fma_f32 v[70:71], v[246:247], v[70:71], v[78:79] op_sel:[1,0,0] neg_lo:[0,0,1] neg_hi:[0,0,1]
	v_cndmask_b32_e64 v79, v197, v71, s[44:45]
	v_cndmask_b32_e64 v78, v196, v70, s[44:45]
	v_cndmask_b32_e64 v77, v199, v69, s[44:45]
	v_cndmask_b32_e64 v76, v198, v68, s[44:45]
	v_cvt_pk_bf16_f32 v28, v80, v81
	v_cvt_pk_bf16_f32 v29, v82, v83
	v_cvt_pk_bf16_f32 v30, v76, v77
	v_cvt_pk_bf16_f32 v31, v78, v79
	v_pk_mul_f32 v[196:197], v[248:249], v[242:243] op_sel:[1,0]
	v_pk_mul_f32 v[198:199], v[248:249], v[240:241] op_sel:[1,0]
	v_pk_mul_f32 v[242:243], v[248:249], v[242:243] op_sel_hi:[0,1]
	v_pk_mul_f32 v[240:241], v[248:249], v[240:241] op_sel_hi:[0,1]
	v_pk_fma_f32 v[198:199], v[248:249], v[232:233], v[198:199] op_sel_hi:[0,1,1]
	v_pk_fma_f32 v[196:197], v[248:249], v[234:235], v[196:197] op_sel_hi:[0,1,1]
	v_pk_fma_f32 v[232:233], v[248:249], v[232:233], v[240:241] op_sel:[1,0,0] neg_lo:[0,0,1] neg_hi:[0,0,1]
	v_pk_fma_f32 v[234:235], v[248:249], v[234:235], v[242:243] op_sel:[1,0,0] neg_lo:[0,0,1] neg_hi:[0,0,1]
	v_cndmask_b32_e64 v243, v197, v235, s[44:45]
	v_cndmask_b32_e64 v242, v196, v234, s[44:45]
	v_cndmask_b32_e64 v241, v199, v233, s[44:45]
	v_cndmask_b32_e64 v240, v198, v232, s[44:45]
	v_pk_mul_f32 v[196:197], v[248:249], v[238:239] op_sel:[1,0]
	v_pk_mul_f32 v[198:199], v[248:249], v[236:237] op_sel:[1,0]
	v_pk_mul_f32 v[238:239], v[248:249], v[238:239] op_sel_hi:[0,1]
	v_pk_mul_f32 v[236:237], v[248:249], v[236:237] op_sel_hi:[0,1]
	v_pk_fma_f32 v[198:199], v[248:249], v[228:229], v[198:199] op_sel_hi:[0,1,1]
	v_pk_fma_f32 v[196:197], v[248:249], v[230:231], v[196:197] op_sel_hi:[0,1,1]
	v_pk_fma_f32 v[228:229], v[248:249], v[228:229], v[236:237] op_sel:[1,0,0] neg_lo:[0,0,1] neg_hi:[0,0,1]
	v_pk_fma_f32 v[230:231], v[248:249], v[230:231], v[238:239] op_sel:[1,0,0] neg_lo:[0,0,1] neg_hi:[0,0,1]
	v_cndmask_b32_e64 v239, v197, v231, s[44:45]
	v_cndmask_b32_e64 v238, v196, v230, s[44:45]
	v_cndmask_b32_e64 v237, v199, v229, s[44:45]
	v_cndmask_b32_e64 v236, v198, v228, s[44:45]
	v_cvt_pk_bf16_f32 v32, v240, v241
	v_cvt_pk_bf16_f32 v33, v242, v243
	v_cvt_pk_bf16_f32 v34, v236, v237
	v_cvt_pk_bf16_f32 v35, v238, v239
